# second measurement of the leading-half static priority variant (v48) to choose between the two static-priority forms
# speedup vs baseline: 1.0098x; 1.0018x over previous
; __device__ __forceinline__ int mk_lane() { int l; asm volatile("v_mbcnt_lo_u32_b32 %0, -1, 0\n\tv_mbcnt_hi_u32_b32 %0, -1, %0" : "=v"(l)); return l; }
; #define PG8_STAGE(bufoff, gbase, voff) do { _Pragma("unroll") for (int _i = 0; _i < 2; ++_i) glds16_s((gbase), (voff)[_i], ldsb + (unsigned)((bufoff) + _i * 8192)); } while (0)
; #define PG8_WAIT_V(n) asm volatile("s_waitcnt vmcnt(" #n ")" ::: "memory")
; template <class Prob, class Epi, bool I8 = false, bool ALIGN_EPI = true, bool SP2 = true>
; __device__ __forceinline__ void gemm_phase(LAS unsigned char* lds, int wave, const Prob& P, const Epi& E) {
;     const int tid_ = wave * 64 + mk_lane();
;     const int tid = tid_, wid = __builtin_amdgcn_readfirstlane(tid >> 6), lane = tid & 63, wr = wid >> 2, wc = wid & 3, fr = lane & 15, fq = lane >> 4;
;     const int K = P.K, nt = K / BK;
;     unsigned voffA[2], voffB[2];
; #pragma unroll
;     for (int i = 0; i < 2; ++i) { int R, C; stage_rc(tid * 16 + i * 8192, R, C); const int Rb = (R & ~31) + perm32(R & 31);
;         voffA[i] = P.a_rowoff(R) + (unsigned)C * 2u; voffB[i] = P.b_rowoff(Rb) + (unsigned)C * 2u; }
;     const size_t kstep = (size_t)(BK * 2);
;     const size_t hstepA = P.a_hstep(), hstepB = P.b_hstep();
;     const unsigned ldsw = (unsigned)wid * 1024u;
;     const unsigned ldsb = (unsigned)(size_t)lds + ldsw;
;     const int aoff = lds_byte(wr * 64 + fr, fq * 8), boff = lds_byte(wc * 32 + fr, fq * 8);
;     ...
;     Unit cur, nxt; int ui = 0;
;     if (!P.next(0, cur)) return;
;     Acc acc;
; #pragma unroll
;     for (int a = 0; a < 2; ++a)
; #pragma unroll
;         for (int b = 0; b < 2; ++b)
; #pragma unroll
;             for (int m = 0; m < 4; ++m)
; #pragma unroll
;                 for (int n = 0; n < 2; ++n) acc[a][b][m][n] = (f32x4){0.f, 0.f, 0.f, 0.f};
;     h16x8 At[4][2], B0[2][2], B1[2][2];
;     const char* cA = P.a_tile(cur); const char* cB = P.b_tile(cur);
;     if constexpr (SP2) {
;         PG8_STAGE(PG8_SB(0, 0), cB, voffB); PG8_STAGE(PG8_SB(0, 1), cB + hstepB, voffB); PG8_STAGE(PG8_SA(0, 0), cA, voffA); PG8_STAGE(PG8_SA(0, 1), cA + hstepA, voffA);
;         if (wr == 1) PG8_BAR;
;         PG8_WAIT_V(2); PG8_BAR;
;         PG8_STAGE(PG8_SB(1, 0), cB + kstep, voffB); PG8_STAGE(PG8_SA(1, 0), cA + kstep, voffA); PG8_STAGE(PG8_SB(1, 1), cB + hstepB + kstep, voffB);
;         PG8_WAIT_V(6); PG8_BAR;
.LBB0_215:
	s_mov_b64 s[52:53], 0
	s_add_u32 s30, s96, s52
	s_addc_u32 s31, s97, s53
	s_add_u32 s54, s30, 0x1b200000
	s_mov_b64 s[14:15], -1
	s_addc_u32 s55, s31, 0
	v_writelane_b32 v253, s0, 63
	s_and_b64 vcc, exec, s[0:1]
	s_nop 0
	v_writelane_b32 v255, s1, 0
	s_cbranch_vccnz .LBB0_526
	v_readlane_b32 s0, v254, 42
	v_readlane_b32 s4, v254, 43
	s_add_u32 s26, s30, 0x2d200000
	v_mbcnt_lo_u32_b32 v0, -1, 0
	v_mbcnt_hi_u32_b32 v0, -1, v0
	v_readlane_b32 s5, v254, 44
	v_add_u32_e32 v1, s0, v0
	s_addc_u32 s27, s31, 0
	v_readfirstlane_b32 s0, v1
	s_and_b64 vcc, exec, s[4:5]
	s_cbranch_vccz .LBB0_232
	v_ashrrev_i32_e32 v3, 31, v1
	v_lshrrev_b32_e32 v3, 26, v3
	v_lshlrev_b32_e32 v2, 4, v1
	v_add_u32_e32 v3, v1, v3
	v_bfe_i32 v1, v1, 27, 1
	v_lshrrev_b32_e32 v1, 22, v1
	v_add_u32_e32 v1, v2, v1
	v_and_b32_e32 v1, 0xfffffc00, v1
	v_sub_u32_e32 v1, v2, v1
	v_lshrrev_b32_e32 v4, 4, v1
	v_bitop3_b32 v1, v4, v1, 32 bitop3:0x6c
	s_add_u32 s2, s30, 0x5200000
	v_ashrrev_i32_e32 v5, 31, v1
	s_addc_u32 s19, s31, 0
	v_readlane_b32 s4, v254, 51
	v_ashrrev_i32_e32 v3, 6, v3
	v_lshrrev_b32_e32 v5, 26, v5
	v_readlane_b32 s5, v254, 52
	s_add_u32 s1, s54, s4
	v_lshlrev_b32_e32 v4, 3, v3
	v_add_u32_e32 v5, v1, v5
	s_addc_u32 s4, s55, s5
	v_readlane_b32 s5, v254, 48
	v_and_b32_e32 v4, -16, v4
	v_ashrrev_i32_e32 v6, 6, v5
	v_and_b32_e32 v5, 0xc0, v5
	s_add_u32 s44, s1, s5
	v_add_u32_e32 v4, v6, v4
	v_sub_u32_e32 v1, v1, v5
	v_mov_b32_e32 v8, 1
	s_addc_u32 s45, s4, 0
	v_lshlrev_b32_e32 v3, 5, v3
	v_ashrrev_i16_sdwa v1, v8, sext(v1) dst_sel:DWORD dst_unused:UNUSED_PAD src0_sel:DWORD src1_sel:BYTE_0
	v_lshlrev_b32_e32 v5, 1, v4
	v_lshrrev_b32_e32 v7, 2, v4
	v_and_b32_e32 v6, 3, v6
	s_mov_b32 s4, 0xfffe0
	v_and_b32_e32 v3, 32, v3
	v_bfe_i32 v1, v1, 0, 16
	v_and_b32_e32 v5, 24, v5
	v_and_b32_e32 v7, 4, v7
	v_and_or_b32 v6, v4, s4, v6
	v_or3_b32 v5, v6, v7, v5
	v_add_lshl_u32 v1, v3, v1, 1
	v_lshl_add_u32 v128, v4, 10, v1
	v_lshl_add_u32 v129, v5, 12, v1
	v_add_u32_e32 v1, 0x2000, v2
	v_ashrrev_i32_e32 v2, 31, v1
	v_lshrrev_b32_e32 v2, 22, v2
	v_add_u32_e32 v2, v1, v2
	v_ashrrev_i32_e32 v2, 10, v2
	v_mul_i32_i24_e32 v3, 0x400, v2
	v_sub_u32_e32 v1, v1, v3
	v_lshrrev_b32_e32 v3, 4, v1
	v_bitop3_b32 v1, v3, v1, 32 bitop3:0x6c
	v_ashrrev_i32_e32 v4, 31, v1
	v_lshrrev_b32_e32 v4, 26, v4
	v_lshlrev_b32_e32 v3, 3, v2
	v_add_u32_e32 v4, v1, v4
	v_readlane_b32 s1, v254, 46
	v_and_b32_e32 v3, -16, v3
	v_ashrrev_i32_e32 v5, 6, v4
	s_add_u32 s42, s2, s1
	v_add_u32_e32 v3, v5, v3
	v_and_b32_e32 v5, 3, v5
	s_addc_u32 s43, s19, 0
	v_and_or_b32 v5, v3, s4, v5
	s_ashr_i32 s4, s0, 6
	s_lshl_b32 s5, s4, 10
	s_ashr_i32 s1, s0, 8
	v_and_b32_e32 v4, 0xc0, v4
	s_add_i32 s56, s5, 0
	v_sub_u32_e32 v1, v1, v4
	s_add_u32 s14, s42, 0x20000
	v_lshlrev_b32_e32 v2, 5, v2
	v_ashrrev_i16_sdwa v1, v8, sext(v1) dst_sel:DWORD dst_unused:UNUSED_PAD src0_sel:DWORD src1_sel:BYTE_0
	v_lshlrev_b32_e32 v4, 1, v3
	v_lshrrev_b32_e32 v6, 2, v3
	s_addc_u32 s15, s43, 0
	v_and_b32_e32 v2, 32, v2
	v_bfe_i32 v1, v1, 0, 16
	v_and_b32_e32 v4, 24, v4
	v_and_b32_e32 v6, 4, v6
	s_add_u32 s16, s44, 0x80000
	v_or3_b32 v4, v5, v6, v4
	v_add_lshl_u32 v1, v2, v1, 1
	s_addc_u32 s17, s45, 0
	s_add_i32 s57, s56, 0x10000
	s_mov_b32 s5, m0
	s_mov_b32 m0, s57
	s_nop 0
	global_load_lds_dwordx4 v129, s[44:45]
	s_mov_b32 m0, s5
	v_lshl_add_u32 v131, v4, 12, v1
	s_add_i32 s60, s56, 0x12000
	s_mov_b32 s5, m0
	s_mov_b32 m0, s60
	s_nop 0
	global_load_lds_dwordx4 v131, s[44:45]
	s_mov_b32 m0, s5
	s_add_i32 s61, s56, 0x14000
	s_mov_b32 s5, m0
	s_mov_b32 m0, s61
	s_nop 0
	global_load_lds_dwordx4 v129, s[16:17]
	s_mov_b32 m0, s5
	s_add_i32 s62, s56, 0x16000
	s_mov_b32 s5, m0
	s_mov_b32 m0, s62
	s_nop 0
	global_load_lds_dwordx4 v131, s[16:17]
	s_mov_b32 m0, s5
	v_lshl_add_u32 v130, v3, 10, v1
	s_mov_b32 s5, m0
	s_mov_b32 m0, s56
	s_nop 0
	global_load_lds_dwordx4 v128, s[42:43]
	s_mov_b32 m0, s5
	s_add_i32 s63, s56, 0x2000
	s_mov_b32 s5, m0
	s_mov_b32 m0, s63
	s_nop 0
	global_load_lds_dwordx4 v130, s[42:43]
	s_mov_b32 m0, s5
	s_add_i32 s64, s56, 0x4000
	s_mov_b32 s5, m0
	s_mov_b32 m0, s64
	s_nop 0
	global_load_lds_dwordx4 v128, s[14:15]
	s_mov_b32 m0, s5
	s_add_i32 s68, s56, 0x6000
	s_mov_b32 s5, m0
	s_mov_b32 m0, s68
	s_nop 0
	global_load_lds_dwordx4 v130, s[14:15]
	s_mov_b32 m0, s5
	s_cmp_eq_u32 s1, 1
	s_cselect_b64 s[14:15], -1, 0
	s_setprio 1
	s_cmp_lg_u32 s1, 1
	s_cbranch_scc1 .LBB0_219
	s_barrier
	s_setprio 0

; __device__ __forceinline__ int mk_lane() { int l; asm volatile("v_mbcnt_lo_u32_b32 %0, -1, 0\n\tv_mbcnt_hi_u32_b32 %0, -1, %0" : "=v"(l)); return l; }
; #define PG8_STAGE(bufoff, gbase, voff) do { _Pragma("unroll") for (int _i = 0; _i < 2; ++_i) glds16_s((gbase), (voff)[_i], ldsb + (unsigned)((bufoff) + _i * 8192)); } while (0)
; #define PG8_WAIT_V(n) asm volatile("s_waitcnt vmcnt(" #n ")" ::: "memory")
; template <class Prob, class Epi, bool I8 = false, bool ALIGN_EPI = true, bool SP2 = true>
; __device__ __forceinline__ void gemm_phase(LAS unsigned char* lds, int wave, const Prob& P, const Epi& E) {
;     const int tid_ = wave * 64 + mk_lane();
;     const int tid = tid_, wid = __builtin_amdgcn_readfirstlane(tid >> 6), lane = tid & 63, wr = wid >> 2, wc = wid & 3, fr = lane & 15, fq = lane >> 4;
;     const int K = P.K, nt = K / BK;
;     unsigned voffA[2], voffB[2];
; #pragma unroll
;     for (int i = 0; i < 2; ++i) { int R, C; stage_rc(tid * 16 + i * 8192, R, C); const int Rb = (R & ~31) + perm32(R & 31);
;         voffA[i] = P.a_rowoff(R) + (unsigned)C * 2u; voffB[i] = P.b_rowoff(Rb) + (unsigned)C * 2u; }
;     const size_t kstep = (size_t)(BK * 2);
;     const size_t hstepA = P.a_hstep(), hstepB = P.b_hstep();
;     const unsigned ldsw = (unsigned)wid * 1024u;
;     const unsigned ldsb = (unsigned)(size_t)lds + ldsw;
;     const int aoff = lds_byte(wr * 64 + fr, fq * 8), boff = lds_byte(wc * 32 + fr, fq * 8);
;     ...
;     Unit cur, nxt; int ui = 0;
;     if (!P.next(0, cur)) return;
;     Acc acc;
; #pragma unroll
;     for (int a = 0; a < 2; ++a)
; #pragma unroll
;         for (int b = 0; b < 2; ++b)
; #pragma unroll
;             for (int m = 0; m < 4; ++m)
; #pragma unroll
;                 for (int n = 0; n < 2; ++n) acc[a][b][m][n] = (f32x4){0.f, 0.f, 0.f, 0.f};
;     h16x8 At[4][2], B0[2][2], B1[2][2];
;     const char* cA = P.a_tile(cur); const char* cB = P.b_tile(cur);
;     if constexpr (SP2) {
;         PG8_STAGE(PG8_SB(0, 0), cB, voffB); PG8_STAGE(PG8_SB(0, 1), cB + hstepB, voffB); PG8_STAGE(PG8_SA(0, 0), cA, voffA); PG8_STAGE(PG8_SA(0, 1), cA + hstepA, voffA);
;         if (wr == 1) PG8_BAR;
;         PG8_WAIT_V(2); PG8_BAR;
;         PG8_STAGE(PG8_SB(1, 0), cB + kstep, voffB); PG8_STAGE(PG8_SA(1, 0), cA + kstep, voffA); PG8_STAGE(PG8_SB(1, 1), cB + hstepB + kstep, voffB);
;         PG8_WAIT_V(6); PG8_BAR;
.LBB0_286:
	s_add_u32 s46, s30, 0x4200000
	s_addc_u32 s47, s31, 0
	v_readlane_b32 s0, v254, 42
	v_readlane_b32 s4, v254, 55
	s_waitcnt lgkmcnt(0)
	s_barrier
	s_add_u32 s42, s30, 0x45200000
	v_mbcnt_lo_u32_b32 v0, -1, 0
	v_mbcnt_hi_u32_b32 v0, -1, v0
	v_readlane_b32 s5, v254, 56
	v_add_u32_e32 v1, s0, v0
	s_addc_u32 s43, s31, 0
	v_readfirstlane_b32 s0, v1
	s_and_b64 vcc, exec, s[4:5]
	s_cbranch_vccz .LBB0_380
	v_ashrrev_i32_e32 v2, 31, v1
	v_lshrrev_b32_e32 v2, 26, v2
	v_lshlrev_b32_e32 v3, 4, v1
	v_add_u32_e32 v2, v1, v2
	v_bfe_i32 v1, v1, 27, 1
	v_lshrrev_b32_e32 v1, 22, v1
	v_add_u32_e32 v1, v3, v1
	v_and_b32_e32 v1, 0xfffffc00, v1
	v_sub_u32_e32 v1, v3, v1
	v_lshrrev_b32_e32 v4, 4, v1
	v_bitop3_b32 v1, v4, v1, 32 bitop3:0x6c
	v_ashrrev_i32_e32 v5, 31, v1
	v_ashrrev_i32_e32 v2, 6, v2
	v_lshrrev_b32_e32 v5, 26, v5
	v_lshlrev_b32_e32 v4, 3, v2
	v_add_u32_e32 v5, v1, v5
	v_and_b32_e32 v4, -16, v4
	v_ashrrev_i32_e32 v6, 6, v5
	v_and_b32_e32 v5, 0xc0, v5
	v_add_u32_e32 v4, v6, v4
	v_sub_u32_e32 v1, v1, v5
	v_mov_b32_e32 v8, 1
	v_lshlrev_b32_e32 v2, 5, v2
	v_ashrrev_i16_sdwa v1, v8, sext(v1) dst_sel:DWORD dst_unused:UNUSED_PAD src0_sel:DWORD src1_sel:BYTE_0
	v_lshlrev_b32_e32 v5, 1, v4
	v_lshrrev_b32_e32 v7, 2, v4
	v_and_b32_e32 v6, 3, v6
	s_mov_b32 s2, 0x1ffffe0
	v_and_b32_e32 v2, 32, v2
	v_bfe_i32 v1, v1, 0, 16
	v_and_b32_e32 v5, 24, v5
	v_and_b32_e32 v7, 4, v7
	v_and_or_b32 v6, v4, s2, v6
	v_or3_b32 v5, v6, v7, v5
	v_add_lshl_u32 v2, v2, v1, 1
	v_add_u32_e32 v1, 0x2000, v3
	v_lshl_add_u32 v148, v4, 13, v2
	v_mad_u64_u32 v[136:137], s[4:5], v5, s21, v[2:3]
	v_ashrrev_i32_e32 v2, 31, v1
	v_lshrrev_b32_e32 v2, 22, v2
	v_add_u32_e32 v2, v1, v2
	v_ashrrev_i32_e32 v2, 10, v2
	v_mul_i32_i24_e32 v3, 0x400, v2
	v_sub_u32_e32 v1, v1, v3
	v_lshrrev_b32_e32 v3, 4, v1
	v_bitop3_b32 v1, v3, v1, 32 bitop3:0x6c
	v_ashrrev_i32_e32 v4, 31, v1
	v_lshrrev_b32_e32 v4, 26, v4
	v_lshlrev_b32_e32 v3, 3, v2
	v_add_u32_e32 v4, v1, v4
	v_and_b32_e32 v3, -16, v3
	v_ashrrev_i32_e32 v5, 6, v4
	v_and_b32_e32 v4, 0xc0, v4
	v_add_u32_e32 v3, v5, v3
	v_sub_u32_e32 v1, v1, v4
	v_lshlrev_b32_e32 v2, 5, v2
	v_ashrrev_i16_sdwa v1, v8, sext(v1) dst_sel:DWORD dst_unused:UNUSED_PAD src0_sel:DWORD src1_sel:BYTE_0
	v_lshlrev_b32_e32 v4, 1, v3
	v_lshrrev_b32_e32 v6, 2, v3
	v_and_b32_e32 v5, 3, v5
	v_and_b32_e32 v2, 32, v2
	v_bfe_i32 v1, v1, 0, 16
	v_and_b32_e32 v4, 24, v4
	v_and_b32_e32 v6, 4, v6
	v_and_or_b32 v5, v3, s2, v5
	v_or3_b32 v4, v5, v6, v4
	v_add_lshl_u32 v2, v2, v1, 1
	v_mad_u64_u32 v[138:139], s[4:5], v4, s21, v[2:3]
	s_ashr_i32 s4, s0, 6
	s_lshl_b32 s2, s4, 10
	v_readlane_b32 s6, v254, 58
	s_ashr_i32 s1, s0, 8
	s_add_i32 s2, s2, 0
	s_mul_i32 s5, s6, 0x820000
	s_add_u32 s5, s26, s5
	s_mul_hi_i32 s6, s6, 0x820000
	v_readlane_b32 s7, v254, 57
	s_addc_u32 s6, s27, s6
	s_mul_i32 s7, s7, 0x208000
	s_add_u32 s38, s5, s7
	s_addc_u32 s39, s6, 0
	s_add_i32 s19, s2, 0x10000
	s_mov_b32 s5, m0
	s_mov_b32 m0, s19
	s_nop 0
	global_load_lds_dwordx4 v136, s[38:39]
	s_mov_b32 m0, s5
	s_add_i32 s60, s2, 0x12000
	s_mov_b32 s5, m0
	s_mov_b32 m0, s60
	s_nop 0
	global_load_lds_dwordx4 v138, s[38:39]
	s_mov_b32 m0, s5
	s_add_u32 s14, s38, 0x104000
	s_addc_u32 s15, s39, 0
	s_add_i32 s61, s2, 0x14000
	s_mov_b32 s5, m0
	s_mov_b32 m0, s61
	s_nop 0
	global_load_lds_dwordx4 v136, s[14:15]
	s_mov_b32 m0, s5
	s_add_i32 s62, s2, 0x16000
	s_mov_b32 s5, m0
	s_mov_b32 m0, s62
	s_nop 0
	global_load_lds_dwordx4 v138, s[14:15]
	s_mov_b32 m0, s5
	v_lshl_add_u32 v137, v3, 13, v2
	v_readlane_b32 s5, v252, 30
	s_add_u32 s14, s46, s5
	s_addc_u32 s15, s47, 0
	s_mov_b32 s5, m0
	s_mov_b32 m0, s2
	s_nop 0
	global_load_lds_dwordx4 v148, s[14:15]
	s_mov_b32 m0, s5
	s_add_i32 s63, s2, 0x2000
	s_mov_b32 s5, m0
	s_mov_b32 m0, s63
	s_nop 0
	global_load_lds_dwordx4 v137, s[14:15]
	s_mov_b32 m0, s5
	s_add_u32 s16, s14, 0x100000
	s_addc_u32 s17, s15, 0
	s_add_i32 s68, s2, 0x4000
	s_mov_b32 s5, m0
	s_mov_b32 m0, s68
	s_nop 0
	global_load_lds_dwordx4 v148, s[16:17]
	s_mov_b32 m0, s5
	s_add_i32 s69, s2, 0x6000
	s_mov_b32 s5, m0
	s_mov_b32 m0, s69
	s_nop 0
	global_load_lds_dwordx4 v137, s[16:17]
	s_mov_b32 m0, s5
	s_cmp_eq_u32 s1, 1
	s_cselect_b64 s[76:77], -1, 0
	s_setprio 1
	s_cmp_lg_u32 s1, 1
	s_cbranch_scc1 .LBB0_289
	s_barrier
	s_setprio 0

; __device__ __forceinline__ int mk_lane() { int l; asm volatile("v_mbcnt_lo_u32_b32 %0, -1, 0\n\tv_mbcnt_hi_u32_b32 %0, -1, %0" : "=v"(l)); return l; }
; #define PG8_STAGE(bufoff, gbase, voff) do { _Pragma("unroll") for (int _i = 0; _i < 2; ++_i) glds16_s((gbase), (voff)[_i], ldsb + (unsigned)((bufoff) + _i * 8192)); } while (0)
; #define PG8_WAIT_V(n) asm volatile("s_waitcnt vmcnt(" #n ")" ::: "memory")
; template <class Prob, class Epi, bool I8 = false, bool ALIGN_EPI = true, bool SP2 = true>
; __device__ __forceinline__ void gemm_phase(LAS unsigned char* lds, int wave, const Prob& P, const Epi& E) {
;     const int tid_ = wave * 64 + mk_lane();
;     const int tid = tid_, wid = __builtin_amdgcn_readfirstlane(tid >> 6), lane = tid & 63, wr = wid >> 2, wc = wid & 3, fr = lane & 15, fq = lane >> 4;
;     const int K = P.K, nt = K / BK;
;     unsigned voffA[2], voffB[2];
; #pragma unroll
;     for (int i = 0; i < 2; ++i) { int R, C; stage_rc(tid * 16 + i * 8192, R, C); const int Rb = (R & ~31) + perm32(R & 31);
;         voffA[i] = P.a_rowoff(R) + (unsigned)C * 2u; voffB[i] = P.b_rowoff(Rb) + (unsigned)C * 2u; }
;     const size_t kstep = (size_t)(BK * 2);
;     const size_t hstepA = P.a_hstep(), hstepB = P.b_hstep();
;     const unsigned ldsw = (unsigned)wid * 1024u;
;     const unsigned ldsb = (unsigned)(size_t)lds + ldsw;
;     const int aoff = lds_byte(wr * 64 + fr, fq * 8), boff = lds_byte(wc * 32 + fr, fq * 8);
;     ...
;     Unit cur, nxt; int ui = 0;
;     if (!P.next(0, cur)) return;
;     Acc acc;
; #pragma unroll
;     for (int a = 0; a < 2; ++a)
; #pragma unroll
;         for (int b = 0; b < 2; ++b)
; #pragma unroll
;             for (int m = 0; m < 4; ++m)
; #pragma unroll
;                 for (int n = 0; n < 2; ++n) acc[a][b][m][n] = (f32x4){0.f, 0.f, 0.f, 0.f};
;     h16x8 At[4][2], B0[2][2], B1[2][2];
;     const char* cA = P.a_tile(cur); const char* cB = P.b_tile(cur);
;     if constexpr (SP2) {
;         PG8_STAGE(PG8_SB(0, 0), cB, voffB); PG8_STAGE(PG8_SB(0, 1), cB + hstepB, voffB); PG8_STAGE(PG8_SA(0, 0), cA, voffA); PG8_STAGE(PG8_SA(0, 1), cA + hstepA, voffA);
;         if (wr == 1) PG8_BAR;
;         PG8_WAIT_V(2); PG8_BAR;
;         PG8_STAGE(PG8_SB(1, 0), cB + kstep, voffB); PG8_STAGE(PG8_SA(1, 0), cA + kstep, voffA); PG8_STAGE(PG8_SB(1, 1), cB + hstepB + kstep, voffB);
;         PG8_WAIT_V(6); PG8_BAR;
.LBB0_455:
	v_readlane_b32 s0, v254, 42
	v_readlane_b32 s4, v254, 43
	s_waitcnt lgkmcnt(0)
	s_barrier
	v_mbcnt_lo_u32_b32 v0, -1, 0
	v_mbcnt_hi_u32_b32 v0, -1, v0
	v_readlane_b32 s5, v254, 44
	v_add_u32_e32 v1, s0, v0
	s_and_b64 vcc, exec, s[4:5]
	v_readfirstlane_b32 s0, v1
	s_cbranch_vccz .LBB0_471
	v_ashrrev_i32_e32 v3, 31, v1
	v_lshrrev_b32_e32 v3, 26, v3
	v_lshlrev_b32_e32 v2, 4, v1
	v_add_u32_e32 v3, v1, v3
	v_bfe_i32 v1, v1, 27, 1
	v_lshrrev_b32_e32 v1, 22, v1
	v_add_u32_e32 v1, v2, v1
	v_and_b32_e32 v1, 0xfffffc00, v1
	v_sub_u32_e32 v1, v2, v1
	v_lshrrev_b32_e32 v4, 4, v1
	v_bitop3_b32 v1, v4, v1, 32 bitop3:0x6c
	v_ashrrev_i32_e32 v5, 31, v1
	v_readlane_b32 s1, v253, 52
	v_ashrrev_i32_e32 v3, 6, v3
	v_lshrrev_b32_e32 v5, 26, v5
	s_add_u32 s1, s30, s1
	v_lshlrev_b32_e32 v4, 3, v3
	v_add_u32_e32 v5, v1, v5
	s_addc_u32 s4, s31, 0
	v_and_b32_e32 v4, -16, v4
	v_ashrrev_i32_e32 v6, 6, v5
	v_and_b32_e32 v5, 0xc0, v5
	s_add_u32 s2, s1, 0x9a00000
	v_add_u32_e32 v4, v6, v4
	v_sub_u32_e32 v1, v1, v5
	v_mov_b32_e32 v8, 1
	s_addc_u32 s19, s4, 0
	v_lshlrev_b32_e32 v3, 5, v3
	v_ashrrev_i16_sdwa v1, v8, sext(v1) dst_sel:DWORD dst_unused:UNUSED_PAD src0_sel:DWORD src1_sel:BYTE_0
	v_lshlrev_b32_e32 v5, 1, v4
	v_lshrrev_b32_e32 v7, 2, v4
	v_and_b32_e32 v6, 3, v6
	s_mov_b32 s4, 0xfffe0
	v_and_b32_e32 v3, 32, v3
	v_bfe_i32 v1, v1, 0, 16
	v_and_b32_e32 v5, 24, v5
	v_and_b32_e32 v7, 4, v7
	v_and_or_b32 v6, v4, s4, v6
	v_or3_b32 v5, v6, v7, v5
	v_add_lshl_u32 v1, v3, v1, 1
	v_lshl_add_u32 v142, v4, 12, v1
	v_lshl_add_u32 v143, v5, 12, v1
	v_add_u32_e32 v1, 0x2000, v2
	v_ashrrev_i32_e32 v2, 31, v1
	v_lshrrev_b32_e32 v2, 22, v2
	v_add_u32_e32 v2, v1, v2
	v_ashrrev_i32_e32 v2, 10, v2
	v_mul_i32_i24_e32 v3, 0x400, v2
	v_sub_u32_e32 v1, v1, v3
	v_lshrrev_b32_e32 v3, 4, v1
	v_bitop3_b32 v1, v3, v1, 32 bitop3:0x6c
	v_ashrrev_i32_e32 v4, 31, v1
	v_lshrrev_b32_e32 v4, 26, v4
	v_lshlrev_b32_e32 v3, 3, v2
	v_add_u32_e32 v4, v1, v4
	v_and_b32_e32 v3, -16, v3
	v_ashrrev_i32_e32 v5, 6, v4
	v_add_u32_e32 v3, v5, v3
	v_and_b32_e32 v5, 3, v5
	v_and_b32_e32 v4, 0xc0, v4
	v_and_or_b32 v5, v3, s4, v5
	s_ashr_i32 s4, s0, 6
	v_sub_u32_e32 v1, v1, v4
	s_lshl_b32 s5, s4, 10
	s_ashr_i32 s1, s0, 8
	v_lshlrev_b32_e32 v2, 5, v2
	v_ashrrev_i16_sdwa v1, v8, sext(v1) dst_sel:DWORD dst_unused:UNUSED_PAD src0_sel:DWORD src1_sel:BYTE_0
	v_lshlrev_b32_e32 v4, 1, v3
	v_lshrrev_b32_e32 v6, 2, v3
	s_add_i32 s50, s5, 0
	v_readlane_b32 s6, v252, 32
	v_and_b32_e32 v2, 32, v2
	v_bfe_i32 v1, v1, 0, 16
	v_and_b32_e32 v4, 24, v4
	v_and_b32_e32 v6, 4, v6
	v_readlane_b32 s7, v252, 33
	s_add_u32 s40, s2, s6
	v_or3_b32 v4, v5, v6, v4
	v_add_lshl_u32 v1, v2, v1, 1
	s_addc_u32 s41, s19, s7
	s_add_i32 s51, s50, 0x10000
	s_mov_b32 s5, m0
	s_mov_b32 m0, s51
	s_nop 0
	global_load_lds_dwordx4 v143, s[40:41]
	s_mov_b32 m0, s5
	s_add_i32 s56, s50, 0x12000
	v_lshl_add_u32 v145, v4, 12, v1
	s_mov_b32 s5, m0
	s_mov_b32 m0, s56
	s_nop 0
	global_load_lds_dwordx4 v145, s[40:41]
	s_mov_b32 m0, s5
	s_add_u32 s14, s40, 0x80000
	s_addc_u32 s15, s41, 0
	s_add_i32 s57, s50, 0x14000
	s_mov_b32 s5, m0
	s_mov_b32 m0, s57
	s_nop 0
	global_load_lds_dwordx4 v143, s[14:15]
	s_mov_b32 m0, s5
	s_add_i32 s60, s50, 0x16000
	v_readlane_b32 s6, v252, 38
	s_mov_b32 s5, m0
	s_mov_b32 m0, s60
	s_nop 0
	global_load_lds_dwordx4 v145, s[14:15]
	s_mov_b32 m0, s5
	v_readlane_b32 s7, v252, 39
	s_add_u32 s44, s42, s6
	s_addc_u32 s45, s43, s7
	s_mov_b32 s5, m0
	s_mov_b32 m0, s50
	s_nop 0
	global_load_lds_dwordx4 v142, s[44:45]
	s_mov_b32 m0, s5
	s_add_i32 s61, s50, 0x2000
	v_lshl_add_u32 v144, v3, 12, v1
	s_mov_b32 s5, m0
	s_mov_b32 m0, s61
	s_nop 0
	global_load_lds_dwordx4 v144, s[44:45]
	s_mov_b32 m0, s5
	s_add_u32 s14, s44, 0x80000
	s_addc_u32 s15, s45, 0
	s_add_i32 s62, s50, 0x4000
	s_mov_b32 s5, m0
	s_mov_b32 m0, s62
	s_nop 0
	global_load_lds_dwordx4 v142, s[14:15]
	s_mov_b32 m0, s5
	s_add_i32 s63, s50, 0x6000
	s_mov_b32 s5, m0
	s_mov_b32 m0, s63
	s_nop 0
	global_load_lds_dwordx4 v144, s[14:15]
	s_mov_b32 m0, s5
	s_cmp_eq_u32 s1, 1
	s_cselect_b64 s[14:15], -1, 0
	s_setprio 1
	s_cmp_lg_u32 s1, 1
	s_cbranch_scc1 .LBB0_458
	s_barrier
	s_setprio 0

; __device__ __forceinline__ int mk_lane() { int l; asm volatile("v_mbcnt_lo_u32_b32 %0, -1, 0\n\tv_mbcnt_hi_u32_b32 %0, -1, %0" : "=v"(l)); return l; }
; #define PG8_STAGE(bufoff, gbase, voff) do { _Pragma("unroll") for (int _i = 0; _i < 2; ++_i) glds16_s((gbase), (voff)[_i], ldsb + (unsigned)((bufoff) + _i * 8192)); } while (0)
; #define PG8_WAIT_V(n) asm volatile("s_waitcnt vmcnt(" #n ")" ::: "memory")
; template <class Prob, class Epi, bool I8 = false, bool ALIGN_EPI = true, bool SP2 = true>
; __device__ __forceinline__ void gemm_phase(LAS unsigned char* lds, int wave, const Prob& P, const Epi& E) {
;     const int tid_ = wave * 64 + mk_lane();
;     const int tid = tid_, wid = __builtin_amdgcn_readfirstlane(tid >> 6), lane = tid & 63, wr = wid >> 2, wc = wid & 3, fr = lane & 15, fq = lane >> 4;
;     const int K = P.K, nt = K / BK;
;     unsigned voffA[2], voffB[2];
; #pragma unroll
;     for (int i = 0; i < 2; ++i) { int R, C; stage_rc(tid * 16 + i * 8192, R, C); const int Rb = (R & ~31) + perm32(R & 31);
;         voffA[i] = P.a_rowoff(R) + (unsigned)C * 2u; voffB[i] = P.b_rowoff(Rb) + (unsigned)C * 2u; }
;     const size_t kstep = (size_t)(BK * 2);
;     const size_t hstepA = P.a_hstep(), hstepB = P.b_hstep();
;     const unsigned ldsw = (unsigned)wid * 1024u;
;     const unsigned ldsb = (unsigned)(size_t)lds + ldsw;
;     const int aoff = lds_byte(wr * 64 + fr, fq * 8), boff = lds_byte(wc * 32 + fr, fq * 8);
;     ...
;     Unit cur, nxt; int ui = 0;
;     if (!P.next(0, cur)) return;
;     Acc acc;
; #pragma unroll
;     for (int a = 0; a < 2; ++a)
; #pragma unroll
;         for (int b = 0; b < 2; ++b)
; #pragma unroll
;             for (int m = 0; m < 4; ++m)
; #pragma unroll
;                 for (int n = 0; n < 2; ++n) acc[a][b][m][n] = (f32x4){0.f, 0.f, 0.f, 0.f};
;     h16x8 At[4][2], B0[2][2], B1[2][2];
;     const char* cA = P.a_tile(cur); const char* cB = P.b_tile(cur);
;     if constexpr (SP2) {
;         PG8_STAGE(PG8_SB(0, 0), cB, voffB); PG8_STAGE(PG8_SB(0, 1), cB + hstepB, voffB); PG8_STAGE(PG8_SA(0, 0), cA, voffA); PG8_STAGE(PG8_SA(0, 1), cA + hstepA, voffA);
;         if (wr == 1) PG8_BAR;
;         PG8_WAIT_V(2); PG8_BAR;
;         PG8_STAGE(PG8_SB(1, 0), cB + kstep, voffB); PG8_STAGE(PG8_SA(1, 0), cA + kstep, voffA); PG8_STAGE(PG8_SB(1, 1), cB + hstepB + kstep, voffB);
;         PG8_WAIT_V(6); PG8_BAR;
.LBB0_526:
	s_and_b64 vcc, exec, s[14:15]
	s_cbranch_vccz .LBB0_925
	s_add_u32 s76, s30, 0x3f200000
	s_addc_u32 s77, s31, 0
	s_add_u32 s46, s30, 0x100000
	s_addc_u32 s47, s31, 0
	v_readlane_b32 s0, v254, 42
	v_readlane_b32 s4, v252, 1
	s_add_u32 s26, s30, 0x180000
	v_mbcnt_lo_u32_b32 v0, -1, 0
	v_mbcnt_hi_u32_b32 v0, -1, v0
	v_readlane_b32 s5, v252, 2
	v_add_u32_e32 v1, s0, v0
	s_addc_u32 s27, s31, 0
	v_readfirstlane_b32 s0, v1
	s_and_b64 vcc, exec, s[4:5]
	v_writelane_b32 v255, s93, 1
	s_cbranch_vccz .LBB0_607
	v_ashrrev_i32_e32 v3, 31, v1
	v_lshrrev_b32_e32 v3, 26, v3
	v_lshlrev_b32_e32 v2, 4, v1
	v_add_u32_e32 v3, v1, v3
	v_bfe_i32 v1, v1, 27, 1
	v_lshrrev_b32_e32 v1, 22, v1
	v_add_u32_e32 v1, v2, v1
	v_and_b32_e32 v1, 0xfffffc00, v1
	v_sub_u32_e32 v1, v2, v1
	v_lshrrev_b32_e32 v4, 4, v1
	v_bitop3_b32 v1, v4, v1, 32 bitop3:0x6c
	v_ashrrev_i32_e32 v5, 31, v1
	v_readlane_b32 s1, v253, 53
	v_ashrrev_i32_e32 v3, 6, v3
	v_lshrrev_b32_e32 v5, 26, v5
	s_add_u32 s1, s30, s1
	v_lshlrev_b32_e32 v4, 3, v3
	v_add_u32_e32 v5, v1, v5
	s_addc_u32 s2, s31, 0
	v_and_b32_e32 v4, -16, v4
	v_ashrrev_i32_e32 v6, 6, v5
	v_and_b32_e32 v5, 0xc0, v5
	s_add_u32 s19, s1, 0x5a00000
	v_add_u32_e32 v4, v6, v4
	v_sub_u32_e32 v1, v1, v5
	v_mov_b32_e32 v8, 1
	s_addc_u32 s62, s2, 0
	v_lshlrev_b32_e32 v3, 5, v3
	v_ashrrev_i16_sdwa v1, v8, sext(v1) dst_sel:DWORD dst_unused:UNUSED_PAD src0_sel:DWORD src1_sel:BYTE_0
	v_lshlrev_b32_e32 v5, 1, v4
	v_lshrrev_b32_e32 v7, 2, v4
	v_and_b32_e32 v6, 3, v6
	s_mov_b32 s2, 0xfffe0
	v_and_b32_e32 v3, 32, v3
	v_bfe_i32 v1, v1, 0, 16
	v_and_b32_e32 v5, 24, v5
	v_and_b32_e32 v7, 4, v7
	v_and_or_b32 v6, v4, s2, v6
	v_or3_b32 v5, v6, v7, v5
	v_add_lshl_u32 v1, v3, v1, 1
	v_lshl_add_u32 v132, v4, 12, v1
	v_lshl_add_u32 v133, v5, 12, v1
	v_add_u32_e32 v1, 0x2000, v2
	v_ashrrev_i32_e32 v2, 31, v1
	v_lshrrev_b32_e32 v2, 22, v2
	v_add_u32_e32 v2, v1, v2
	v_ashrrev_i32_e32 v2, 10, v2
	v_mul_i32_i24_e32 v3, 0x400, v2
	v_sub_u32_e32 v1, v1, v3
	v_lshrrev_b32_e32 v3, 4, v1
	v_bitop3_b32 v1, v3, v1, 32 bitop3:0x6c
	v_ashrrev_i32_e32 v4, 31, v1
	v_lshrrev_b32_e32 v4, 26, v4
	v_lshlrev_b32_e32 v3, 3, v2
	v_add_u32_e32 v4, v1, v4
	s_ashr_i32 s1, s0, 6
	v_and_b32_e32 v3, -16, v3
	v_ashrrev_i32_e32 v5, 6, v4
	v_and_b32_e32 v4, 0xc0, v4
	v_add_u32_e32 v3, v5, v3
	v_sub_u32_e32 v1, v1, v4
	v_and_b32_e32 v5, 3, v5
	s_lshl_b32 s63, s1, 10
	v_lshlrev_b32_e32 v2, 5, v2
	v_ashrrev_i16_sdwa v1, v8, sext(v1) dst_sel:DWORD dst_unused:UNUSED_PAD src0_sel:DWORD src1_sel:BYTE_0
	v_lshlrev_b32_e32 v4, 1, v3
	v_lshrrev_b32_e32 v6, 2, v3
	v_and_or_b32 v5, v3, s2, v5
	s_ashr_i32 s2, s0, 8
	s_add_i32 s63, s63, 0
	v_readlane_b32 s4, v252, 46
	v_and_b32_e32 v2, 32, v2
	v_bfe_i32 v1, v1, 0, 16
	v_and_b32_e32 v4, 24, v4
	v_and_b32_e32 v6, 4, v6
	v_readlane_b32 s5, v252, 47
	s_add_u32 s38, s19, s4
	v_or3_b32 v4, v5, v6, v4
	v_add_lshl_u32 v1, v2, v1, 1
	s_addc_u32 s39, s62, s5
	s_add_i32 s64, s63, 0x10000
	s_mov_b32 s4, m0
	s_mov_b32 m0, s64
	s_nop 0
	global_load_lds_dwordx4 v133, s[38:39]
	s_mov_b32 m0, s4
	v_lshl_add_u32 v135, v4, 12, v1
	s_add_i32 s68, s63, 0x12000
	s_mov_b32 s4, m0
	s_mov_b32 m0, s68
	s_nop 0
	global_load_lds_dwordx4 v135, s[38:39]
	s_mov_b32 m0, s4
	s_add_u32 s4, s38, 0x80000
	s_addc_u32 s5, s39, 0
	s_add_i32 s69, s63, 0x14000
	s_mov_b32 s6, m0
	s_mov_b32 m0, s69
	s_nop 0
	global_load_lds_dwordx4 v133, s[4:5]
	s_mov_b32 m0, s6
	s_add_i32 s79, s63, 0x16000
	s_mov_b32 s6, m0
	s_mov_b32 m0, s79
	s_nop 0
	global_load_lds_dwordx4 v135, s[4:5]
	s_mov_b32 m0, s6
	v_readlane_b32 s4, v252, 52
	v_readlane_b32 s5, v252, 53
	s_add_u32 s40, s54, s4
	s_addc_u32 s41, s55, s5
	s_mov_b32 s4, m0
	s_mov_b32 m0, s63
	s_nop 0
	global_load_lds_dwordx4 v132, s[40:41]
	s_mov_b32 m0, s4
	v_lshl_add_u32 v134, v3, 12, v1
	s_add_i32 s80, s63, 0x2000
	s_mov_b32 s4, m0
	s_mov_b32 m0, s80
	s_nop 0
	global_load_lds_dwordx4 v134, s[40:41]
	s_mov_b32 m0, s4
	s_add_u32 s4, s40, 0x80000
	s_addc_u32 s5, s41, 0
	s_add_i32 s81, s63, 0x4000
	s_mov_b32 s6, m0
	s_mov_b32 m0, s81
	s_nop 0
	global_load_lds_dwordx4 v132, s[4:5]
	s_mov_b32 m0, s6
	s_add_i32 s82, s63, 0x6000
	s_mov_b32 s6, m0
	s_mov_b32 m0, s82
	s_nop 0
	global_load_lds_dwordx4 v134, s[4:5]
	s_mov_b32 m0, s6
	s_cmp_eq_u32 s2, 1
	s_cselect_b64 s[16:17], -1, 0
	s_setprio 1
	s_cmp_lg_u32 s2, 1
	s_cbranch_scc1 .LBB0_530
	s_barrier
	s_setprio 0

; __device__ __forceinline__ int mk_lane() { int l; asm volatile("v_mbcnt_lo_u32_b32 %0, -1, 0\n\tv_mbcnt_hi_u32_b32 %0, -1, %0" : "=v"(l)); return l; }
; #define PG8_STAGE(bufoff, gbase, voff) do { _Pragma("unroll") for (int _i = 0; _i < 2; ++_i) glds16_s((gbase), (voff)[_i], ldsb + (unsigned)((bufoff) + _i * 8192)); } while (0)
; #define PG8_WAIT_V(n) asm volatile("s_waitcnt vmcnt(" #n ")" ::: "memory")
; template <class Prob, class Epi, bool I8 = false, bool ALIGN_EPI = true, bool SP2 = true>
; __device__ __forceinline__ void gemm_phase(LAS unsigned char* lds, int wave, const Prob& P, const Epi& E) {
;     const int tid_ = wave * 64 + mk_lane();
;     const int tid = tid_, wid = __builtin_amdgcn_readfirstlane(tid >> 6), lane = tid & 63, wr = wid >> 2, wc = wid & 3, fr = lane & 15, fq = lane >> 4;
;     const int K = P.K, nt = K / BK;
;     unsigned voffA[2], voffB[2];
; #pragma unroll
;     for (int i = 0; i < 2; ++i) { int R, C; stage_rc(tid * 16 + i * 8192, R, C); const int Rb = (R & ~31) + perm32(R & 31);
;         voffA[i] = P.a_rowoff(R) + (unsigned)C * 2u; voffB[i] = P.b_rowoff(Rb) + (unsigned)C * 2u; }
;     const size_t kstep = (size_t)(BK * 2);
;     const size_t hstepA = P.a_hstep(), hstepB = P.b_hstep();
;     const unsigned ldsw = (unsigned)wid * 1024u;
;     const unsigned ldsb = (unsigned)(size_t)lds + ldsw;
;     const int aoff = lds_byte(wr * 64 + fr, fq * 8), boff = lds_byte(wc * 32 + fr, fq * 8);
;     ...
;     Unit cur, nxt; int ui = 0;
;     if (!P.next(0, cur)) return;
;     Acc acc;
; #pragma unroll
;     for (int a = 0; a < 2; ++a)
; #pragma unroll
;         for (int b = 0; b < 2; ++b)
; #pragma unroll
;             for (int m = 0; m < 4; ++m)
; #pragma unroll
;                 for (int n = 0; n < 2; ++n) acc[a][b][m][n] = (f32x4){0.f, 0.f, 0.f, 0.f};
;     h16x8 At[4][2], B0[2][2], B1[2][2];
;     const char* cA = P.a_tile(cur); const char* cB = P.b_tile(cur);
;     if constexpr (SP2) {
;         PG8_STAGE(PG8_SB(0, 0), cB, voffB); PG8_STAGE(PG8_SB(0, 1), cB + hstepB, voffB); PG8_STAGE(PG8_SA(0, 0), cA, voffA); PG8_STAGE(PG8_SA(0, 1), cA + hstepA, voffA);
;         if (wr == 1) PG8_BAR;
;         PG8_WAIT_V(2); PG8_BAR;
;         PG8_STAGE(PG8_SB(1, 0), cB + kstep, voffB); PG8_STAGE(PG8_SA(1, 0), cA + kstep, voffA); PG8_STAGE(PG8_SB(1, 1), cB + hstepB + kstep, voffB);
;         PG8_WAIT_V(6); PG8_BAR;
.LBB0_607:
	v_readlane_b32 s0, v254, 42
	s_waitcnt vmcnt(63) expcnt(7) lgkmcnt(15)
	s_barrier
	v_mbcnt_lo_u32_b32 v0, -1, 0
	v_mbcnt_hi_u32_b32 v0, -1, v0
	s_nop 0
	v_add_u32_e32 v1, s0, v0
	v_readlane_b32 s0, v252, 1
	v_readlane_b32 s1, v252, 2
	s_andn2_b64 vcc, exec, s[0:1]
	v_readfirstlane_b32 s1, v1
	s_cbranch_vccnz .LBB0_647
	v_ashrrev_i32_e32 v3, 31, v1
	v_lshrrev_b32_e32 v3, 26, v3
	v_lshlrev_b32_e32 v2, 4, v1
	v_add_u32_e32 v3, v1, v3
	v_bfe_i32 v1, v1, 27, 1
	v_lshrrev_b32_e32 v1, 22, v1
	v_add_u32_e32 v1, v2, v1
	v_and_b32_e32 v1, 0xfffffc00, v1
	v_sub_u32_e32 v1, v2, v1
	v_lshrrev_b32_e32 v4, 4, v1
	v_bitop3_b32 v1, v4, v1, 32 bitop3:0x6c
	v_ashrrev_i32_e32 v5, 31, v1
	v_ashrrev_i32_e32 v3, 6, v3
	v_lshrrev_b32_e32 v5, 26, v5
	v_lshlrev_b32_e32 v4, 3, v3
	v_add_u32_e32 v5, v1, v5
	v_and_b32_e32 v4, -16, v4
	v_ashrrev_i32_e32 v6, 6, v5
	v_and_b32_e32 v5, 0xc0, v5
	v_add_u32_e32 v4, v6, v4
	v_sub_u32_e32 v1, v1, v5
	v_mov_b32_e32 v8, 1
	v_lshlrev_b32_e32 v3, 5, v3
	v_ashrrev_i16_sdwa v1, v8, sext(v1) dst_sel:DWORD dst_unused:UNUSED_PAD src0_sel:DWORD src1_sel:BYTE_0
	v_lshlrev_b32_e32 v5, 1, v4
	v_lshrrev_b32_e32 v7, 2, v4
	v_and_b32_e32 v6, 3, v6
	s_mov_b32 s2, 0x1fffe0
	v_and_b32_e32 v3, 32, v3
	v_bfe_i32 v1, v1, 0, 16
	v_and_b32_e32 v5, 24, v5
	v_and_b32_e32 v7, 4, v7
	v_and_or_b32 v6, v4, s2, v6
	v_or3_b32 v5, v6, v7, v5
	v_add_lshl_u32 v1, v3, v1, 1
	v_lshl_add_u32 v148, v4, 11, v1
	v_lshl_add_u32 v149, v5, 11, v1
	v_add_u32_e32 v1, 0x2000, v2
	v_ashrrev_i32_e32 v2, 31, v1
	v_lshrrev_b32_e32 v2, 22, v2
	v_add_u32_e32 v2, v1, v2
	v_ashrrev_i32_e32 v2, 10, v2
	v_mul_i32_i24_e32 v3, 0x400, v2
	v_sub_u32_e32 v1, v1, v3
	v_lshrrev_b32_e32 v3, 4, v1
	v_bitop3_b32 v1, v3, v1, 32 bitop3:0x6c
	v_ashrrev_i32_e32 v4, 31, v1
	v_lshrrev_b32_e32 v4, 26, v4
	v_lshlrev_b32_e32 v3, 3, v2
	v_add_u32_e32 v4, v1, v4
	v_and_b32_e32 v3, -16, v3
	v_ashrrev_i32_e32 v5, 6, v4
	s_ashr_i32 s0, s1, 6
	v_add_u32_e32 v3, v5, v3
	v_and_b32_e32 v5, 3, v5
	v_and_or_b32 v5, v3, s2, v5
	s_lshl_b32 s2, s0, 10
	s_ashr_i32 s4, s1, 8
	s_add_i32 s2, s2, 0
	s_add_u32 s19, s30, 0x51200000
	s_addc_u32 s64, s31, 0
	v_readlane_b32 s5, v253, 54
	s_add_u32 s5, s30, s5
	s_addc_u32 s6, s31, 0
	v_and_b32_e32 v4, 0xc0, v4
	s_add_u32 s79, s5, 0xaa00000
	v_sub_u32_e32 v1, v1, v4
	s_addc_u32 s80, s6, 0
	s_ashr_i32 s61, s60, 31
	s_ashr_i32 s39, s38, 31
	v_lshlrev_b32_e32 v2, 5, v2
	v_ashrrev_i16_sdwa v1, v8, sext(v1) dst_sel:DWORD dst_unused:UNUSED_PAD src0_sel:DWORD src1_sel:BYTE_0
	v_lshlrev_b32_e32 v4, 1, v3
	v_lshrrev_b32_e32 v6, 2, v3
	s_lshl_b64 s[14:15], s[60:61], 19
	s_lshl_b64 s[16:17], s[38:39], 19
	v_and_b32_e32 v2, 32, v2
	v_bfe_i32 v1, v1, 0, 16
	v_and_b32_e32 v4, 24, v4
	v_and_b32_e32 v6, 4, v6
	s_add_u32 s44, s79, s16
	v_or3_b32 v4, v5, v6, v4
	v_add_lshl_u32 v1, v2, v1, 1
	s_addc_u32 s45, s80, s17
	s_add_i32 s81, s2, 0x10000
	s_mov_b32 s5, m0
	s_mov_b32 m0, s81
	s_nop 0
	global_load_lds_dwordx4 v149, s[44:45]
	s_mov_b32 m0, s5
	s_add_i32 s82, s2, 0x12000
	v_lshl_add_u32 v151, v4, 11, v1
	s_mov_b32 s5, m0
	s_mov_b32 m0, s82
	s_nop 0
	global_load_lds_dwordx4 v151, s[44:45]
	s_mov_b32 m0, s5
	s_add_u32 s16, s44, 0x40000
	s_addc_u32 s17, s45, 0
	s_add_i32 s83, s2, 0x14000
	s_mov_b32 s5, m0
	s_mov_b32 m0, s83
	s_nop 0
	global_load_lds_dwordx4 v149, s[16:17]
	s_mov_b32 m0, s5
	s_add_i32 s84, s2, 0x16000
	s_mov_b32 s5, m0
	s_mov_b32 m0, s84
	s_nop 0
	global_load_lds_dwordx4 v151, s[16:17]
	s_mov_b32 m0, s5
	s_add_u32 s56, s19, s14
	s_addc_u32 s57, s64, s15
	s_mov_b32 s5, m0
	s_mov_b32 m0, s2
	s_nop 0
	global_load_lds_dwordx4 v148, s[56:57]
	s_mov_b32 m0, s5
	s_add_i32 s85, s2, 0x2000
	v_lshl_add_u32 v150, v3, 11, v1
	s_mov_b32 s5, m0
	s_mov_b32 m0, s85
	s_nop 0
	global_load_lds_dwordx4 v150, s[56:57]
	s_mov_b32 m0, s5
	s_add_u32 s14, s56, 0x40000
	s_addc_u32 s15, s57, 0
	s_add_i32 s86, s2, 0x4000
	s_mov_b32 s5, m0
	s_mov_b32 m0, s86
	s_nop 0
	global_load_lds_dwordx4 v148, s[14:15]
	s_mov_b32 m0, s5
	s_add_i32 s87, s2, 0x6000
	s_mov_b32 s5, m0
	s_mov_b32 m0, s87
	s_nop 0
	global_load_lds_dwordx4 v150, s[14:15]
	s_mov_b32 m0, s5
	s_cmp_eq_u32 s4, 1
	s_cselect_b64 s[14:15], -1, 0
	s_setprio 1
	s_cmp_lg_u32 s4, 1
	s_cbranch_scc1 .LBB0_610
	s_barrier
	s_setprio 0

; __device__ __forceinline__ int mk_lane() { int l; asm volatile("v_mbcnt_lo_u32_b32 %0, -1, 0\n\tv_mbcnt_hi_u32_b32 %0, -1, %0" : "=v"(l)); return l; }
; #define PG8_STAGE(bufoff, gbase, voff) do { _Pragma("unroll") for (int _i = 0; _i < 2; ++_i) glds16_s((gbase), (voff)[_i], ldsb + (unsigned)((bufoff) + _i * 8192)); } while (0)
; #define PG8_WAIT_V(n) asm volatile("s_waitcnt vmcnt(" #n ")" ::: "memory")
; template <class Prob, class Epi, bool I8 = false, bool ALIGN_EPI = true, bool SP2 = true>
; __device__ __forceinline__ void gemm_phase(LAS unsigned char* lds, int wave, const Prob& P, const Epi& E) {
;     const int tid_ = wave * 64 + mk_lane();
;     const int tid = tid_, wid = __builtin_amdgcn_readfirstlane(tid >> 6), lane = tid & 63, wr = wid >> 2, wc = wid & 3, fr = lane & 15, fq = lane >> 4;
;     const int K = P.K, nt = K / BK;
;     unsigned voffA[2], voffB[2];
; #pragma unroll
;     for (int i = 0; i < 2; ++i) { int R, C; stage_rc(tid * 16 + i * 8192, R, C); const int Rb = (R & ~31) + perm32(R & 31);
;         voffA[i] = P.a_rowoff(R) + (unsigned)C * 2u; voffB[i] = P.b_rowoff(Rb) + (unsigned)C * 2u; }
;     const size_t kstep = (size_t)(BK * 2);
;     const size_t hstepA = P.a_hstep(), hstepB = P.b_hstep();
;     const unsigned ldsw = (unsigned)wid * 1024u;
;     const unsigned ldsb = (unsigned)(size_t)lds + ldsw;
;     const int aoff = lds_byte(wr * 64 + fr, fq * 8), boff = lds_byte(wc * 32 + fr, fq * 8);
;     ...
;     Unit cur, nxt; int ui = 0;
;     if (!P.next(0, cur)) return;
;     Acc acc;
; #pragma unroll
;     for (int a = 0; a < 2; ++a)
; #pragma unroll
;         for (int b = 0; b < 2; ++b)
; #pragma unroll
;             for (int m = 0; m < 4; ++m)
; #pragma unroll
;                 for (int n = 0; n < 2; ++n) acc[a][b][m][n] = (f32x4){0.f, 0.f, 0.f, 0.f};
;     h16x8 At[4][2], B0[2][2], B1[2][2];
;     const char* cA = P.a_tile(cur); const char* cB = P.b_tile(cur);
;     if constexpr (SP2) {
;         PG8_STAGE(PG8_SB(0, 0), cB, voffB); PG8_STAGE(PG8_SB(0, 1), cB + hstepB, voffB); PG8_STAGE(PG8_SA(0, 0), cA, voffA); PG8_STAGE(PG8_SA(0, 1), cA + hstepA, voffA);
;         if (wr == 1) PG8_BAR;
;         PG8_WAIT_V(2); PG8_BAR;
;         PG8_STAGE(PG8_SB(1, 0), cB + kstep, voffB); PG8_STAGE(PG8_SA(1, 0), cA + kstep, voffA); PG8_STAGE(PG8_SB(1, 1), cB + hstepB + kstep, voffB);
;         PG8_WAIT_V(6); PG8_BAR;
.LBB0_854:
	v_readlane_b32 s0, v254, 42
	v_readlane_b32 s4, v254, 43
	s_waitcnt lgkmcnt(0)
	s_barrier
	v_mbcnt_lo_u32_b32 v0, -1, 0
	v_mbcnt_hi_u32_b32 v0, -1, v0
	v_readlane_b32 s5, v254, 44
	v_add_u32_e32 v1, s0, v0
	s_and_b64 vcc, exec, s[4:5]
	v_readfirstlane_b32 s0, v1
	s_cbranch_vccz .LBB0_870
	v_ashrrev_i32_e32 v3, 31, v1
	v_lshrrev_b32_e32 v3, 26, v3
	v_lshlrev_b32_e32 v2, 4, v1
	v_add_u32_e32 v3, v1, v3
	v_bfe_i32 v1, v1, 27, 1
	v_lshrrev_b32_e32 v1, 22, v1
	v_add_u32_e32 v1, v2, v1
	v_and_b32_e32 v1, 0xfffffc00, v1
	v_sub_u32_e32 v1, v2, v1
	v_lshrrev_b32_e32 v4, 4, v1
	v_bitop3_b32 v1, v4, v1, 32 bitop3:0x6c
	v_ashrrev_i32_e32 v5, 31, v1
	v_readlane_b32 s1, v253, 52
	v_ashrrev_i32_e32 v3, 6, v3
	v_lshrrev_b32_e32 v5, 26, v5
	s_add_u32 s1, s30, s1
	v_lshlrev_b32_e32 v4, 3, v3
	v_add_u32_e32 v5, v1, v5
	s_addc_u32 s4, s31, 0
	v_and_b32_e32 v4, -16, v4
	v_ashrrev_i32_e32 v6, 6, v5
	v_and_b32_e32 v5, 0xc0, v5
	s_add_u32 s2, s1, 0x8a00000
	v_add_u32_e32 v4, v6, v4
	v_sub_u32_e32 v1, v1, v5
	v_mov_b32_e32 v8, 1
	s_addc_u32 s19, s4, 0
	v_lshlrev_b32_e32 v3, 5, v3
	v_ashrrev_i16_sdwa v1, v8, sext(v1) dst_sel:DWORD dst_unused:UNUSED_PAD src0_sel:DWORD src1_sel:BYTE_0
	v_lshlrev_b32_e32 v5, 1, v4
	v_lshrrev_b32_e32 v7, 2, v4
	v_and_b32_e32 v6, 3, v6
	s_mov_b32 s4, 0xfffe0
	v_and_b32_e32 v3, 32, v3
	v_bfe_i32 v1, v1, 0, 16
	v_and_b32_e32 v5, 24, v5
	v_and_b32_e32 v7, 4, v7
	v_and_or_b32 v6, v4, s4, v6
	v_or3_b32 v5, v6, v7, v5
	v_add_lshl_u32 v1, v3, v1, 1
	v_lshl_add_u32 v142, v4, 12, v1
	v_lshl_add_u32 v143, v5, 12, v1
	v_add_u32_e32 v1, 0x2000, v2
	v_ashrrev_i32_e32 v2, 31, v1
	v_lshrrev_b32_e32 v2, 22, v2
	v_add_u32_e32 v2, v1, v2
	v_ashrrev_i32_e32 v2, 10, v2
	v_mul_i32_i24_e32 v3, 0x400, v2
	v_sub_u32_e32 v1, v1, v3
	v_lshrrev_b32_e32 v3, 4, v1
	v_bitop3_b32 v1, v3, v1, 32 bitop3:0x6c
	v_ashrrev_i32_e32 v4, 31, v1
	v_lshrrev_b32_e32 v4, 26, v4
	v_lshlrev_b32_e32 v3, 3, v2
	v_add_u32_e32 v4, v1, v4
	v_and_b32_e32 v3, -16, v3
	v_ashrrev_i32_e32 v5, 6, v4
	v_add_u32_e32 v3, v5, v3
	v_and_b32_e32 v5, 3, v5
	v_and_b32_e32 v4, 0xc0, v4
	v_and_or_b32 v5, v3, s4, v5
	s_ashr_i32 s4, s0, 6
	v_sub_u32_e32 v1, v1, v4
	s_lshl_b32 s5, s4, 10
	s_ashr_i32 s1, s0, 8
	v_lshlrev_b32_e32 v2, 5, v2
	v_ashrrev_i16_sdwa v1, v8, sext(v1) dst_sel:DWORD dst_unused:UNUSED_PAD src0_sel:DWORD src1_sel:BYTE_0
	v_lshlrev_b32_e32 v4, 1, v3
	v_lshrrev_b32_e32 v6, 2, v3
	s_add_i32 s48, s5, 0
	v_readlane_b32 s6, v252, 32
	v_and_b32_e32 v2, 32, v2
	v_bfe_i32 v1, v1, 0, 16
	v_and_b32_e32 v4, 24, v4
	v_and_b32_e32 v6, 4, v6
	v_readlane_b32 s7, v252, 33
	s_add_u32 s40, s2, s6
	v_or3_b32 v4, v5, v6, v4
	v_add_lshl_u32 v1, v2, v1, 1
	s_addc_u32 s41, s19, s7
	s_add_i32 s49, s48, 0x10000
	s_mov_b32 s5, m0
	s_mov_b32 m0, s49
	s_nop 0
	global_load_lds_dwordx4 v143, s[40:41]
	s_mov_b32 m0, s5
	s_add_i32 s50, s48, 0x12000
	v_lshl_add_u32 v145, v4, 12, v1
	s_mov_b32 s5, m0
	s_mov_b32 m0, s50
	s_nop 0
	global_load_lds_dwordx4 v145, s[40:41]
	s_mov_b32 m0, s5
	s_add_u32 s14, s40, 0x80000
	s_addc_u32 s15, s41, 0
	s_add_i32 s51, s48, 0x14000
	s_mov_b32 s5, m0
	s_mov_b32 m0, s51
	s_nop 0
	global_load_lds_dwordx4 v143, s[14:15]
	s_mov_b32 m0, s5
	s_add_i32 s56, s48, 0x16000
	v_readlane_b32 s6, v252, 38
	s_mov_b32 s5, m0
	s_mov_b32 m0, s56
	s_nop 0
	global_load_lds_dwordx4 v145, s[14:15]
	s_mov_b32 m0, s5
	v_readlane_b32 s7, v252, 39
	s_add_u32 s42, s76, s6
	s_addc_u32 s43, s77, s7
	s_mov_b32 s5, m0
	s_mov_b32 m0, s48
	s_nop 0
	global_load_lds_dwordx4 v142, s[42:43]
	s_mov_b32 m0, s5
	s_add_i32 s57, s48, 0x2000
	v_lshl_add_u32 v144, v3, 12, v1
	s_mov_b32 s5, m0
	s_mov_b32 m0, s57
	s_nop 0
	global_load_lds_dwordx4 v144, s[42:43]
	s_mov_b32 m0, s5
	s_add_u32 s14, s42, 0x80000
	s_addc_u32 s15, s43, 0
	s_add_i32 s60, s48, 0x4000
	s_mov_b32 s5, m0
	s_mov_b32 m0, s60
	s_nop 0
	global_load_lds_dwordx4 v142, s[14:15]
	s_mov_b32 m0, s5
	s_add_i32 s61, s48, 0x6000
	s_mov_b32 s5, m0
	s_mov_b32 m0, s61
	s_nop 0
	global_load_lds_dwordx4 v144, s[14:15]
	s_mov_b32 m0, s5
	s_cmp_eq_u32 s1, 1
	s_cselect_b64 s[14:15], -1, 0
	s_setprio 1
	s_cmp_lg_u32 s1, 1
	s_cbranch_scc1 .LBB0_857
	s_barrier
	s_setprio 0

; __device__ __forceinline__ int mk_lane() { int l; asm volatile("v_mbcnt_lo_u32_b32 %0, -1, 0\n\tv_mbcnt_hi_u32_b32 %0, -1, %0" : "=v"(l)); return l; }
; #define PG8_STAGE(bufoff, gbase, voff) do { _Pragma("unroll") for (int _i = 0; _i < 2; ++_i) glds16_s((gbase), (voff)[_i], ldsb + (unsigned)((bufoff) + _i * 8192)); } while (0)
; #define PG8_WAIT_V(n) asm volatile("s_waitcnt vmcnt(" #n ")" ::: "memory")
; template <class Prob, class Epi, bool I8 = false, bool ALIGN_EPI = true, bool SP2 = true>
; __device__ __forceinline__ void gemm_phase(LAS unsigned char* lds, int wave, const Prob& P, const Epi& E) {
;     const int tid_ = wave * 64 + mk_lane();
;     const int tid = tid_, wid = __builtin_amdgcn_readfirstlane(tid >> 6), lane = tid & 63, wr = wid >> 2, wc = wid & 3, fr = lane & 15, fq = lane >> 4;
;     const int K = P.K, nt = K / BK;
;     unsigned voffA[2], voffB[2];
; #pragma unroll
;     for (int i = 0; i < 2; ++i) { int R, C; stage_rc(tid * 16 + i * 8192, R, C); const int Rb = (R & ~31) + perm32(R & 31);
;         voffA[i] = P.a_rowoff(R) + (unsigned)C * 2u; voffB[i] = P.b_rowoff(Rb) + (unsigned)C * 2u; }
;     const size_t kstep = (size_t)(BK * 2);
;     const size_t hstepA = P.a_hstep(), hstepB = P.b_hstep();
;     const unsigned ldsw = (unsigned)wid * 1024u;
;     const unsigned ldsb = (unsigned)(size_t)lds + ldsw;
;     const int aoff = lds_byte(wr * 64 + fr, fq * 8), boff = lds_byte(wc * 32 + fr, fq * 8);
;     ...
;     Unit cur, nxt; int ui = 0;
;     if (!P.next(0, cur)) return;
;     Acc acc;
; #pragma unroll
;     for (int a = 0; a < 2; ++a)
; #pragma unroll
;         for (int b = 0; b < 2; ++b)
; #pragma unroll
;             for (int m = 0; m < 4; ++m)
; #pragma unroll
;                 for (int n = 0; n < 2; ++n) acc[a][b][m][n] = (f32x4){0.f, 0.f, 0.f, 0.f};
;     h16x8 At[4][2], B0[2][2], B1[2][2];
;     const char* cA = P.a_tile(cur); const char* cB = P.b_tile(cur);
;     if constexpr (SP2) {
;         PG8_STAGE(PG8_SB(0, 0), cB, voffB); PG8_STAGE(PG8_SB(0, 1), cB + hstepB, voffB); PG8_STAGE(PG8_SA(0, 0), cA, voffA); PG8_STAGE(PG8_SA(0, 1), cA + hstepA, voffA);
;         if (wr == 1) PG8_BAR;
;         PG8_WAIT_V(2); PG8_BAR;
;         PG8_STAGE(PG8_SB(1, 0), cB + kstep, voffB); PG8_STAGE(PG8_SA(1, 0), cA + kstep, voffA); PG8_STAGE(PG8_SB(1, 1), cB + hstepB + kstep, voffB);
;         PG8_WAIT_V(6); PG8_BAR;
.LBB0_986:
	s_add_u32 s26, s30, 0x240000
	v_readlane_b32 s0, v255, 1
	s_addc_u32 s27, s31, 0
	s_mul_i32 s0, s0, 0x1600000
	s_add_u32 s0, s30, s0
	s_addc_u32 s1, s31, 0
	s_add_u32 s79, s0, 0x57200000
	s_addc_u32 s40, s1, 0
	s_add_u32 s41, s30, 0x51200000
	s_addc_u32 s19, s31, 0
	v_readlane_b32 s0, v254, 42
	v_readlane_b32 s4, v252, 13
	s_waitcnt lgkmcnt(0)
	s_barrier
	s_add_u32 s38, s30, 0x2000000
	v_mbcnt_lo_u32_b32 v0, -1, 0
	v_mbcnt_hi_u32_b32 v0, -1, v0
	v_readlane_b32 s5, v252, 14
	v_add_u32_e32 v1, s0, v0
	s_addc_u32 s39, s31, 0
	v_readfirstlane_b32 s0, v1
	s_and_b64 vcc, exec, s[4:5]
	s_cbranch_vccz .LBB0_1002
	v_ashrrev_i32_e32 v3, 31, v1
	v_lshrrev_b32_e32 v3, 26, v3
	v_lshlrev_b32_e32 v2, 4, v1
	v_add_u32_e32 v3, v1, v3
	v_bfe_i32 v1, v1, 27, 1
	v_lshrrev_b32_e32 v1, 22, v1
	v_add_u32_e32 v1, v2, v1
	v_and_b32_e32 v1, 0xfffffc00, v1
	v_sub_u32_e32 v1, v2, v1
	v_lshrrev_b32_e32 v4, 4, v1
	v_bitop3_b32 v1, v4, v1, 32 bitop3:0x6c
	v_ashrrev_i32_e32 v5, 31, v1
	v_ashrrev_i32_e32 v3, 6, v3
	v_lshrrev_b32_e32 v5, 26, v5
	v_lshlrev_b32_e32 v4, 3, v3
	v_add_u32_e32 v5, v1, v5
	v_and_b32_e32 v4, -16, v4
	v_ashrrev_i32_e32 v6, 6, v5
	v_add_u32_e32 v4, v6, v4
	v_and_b32_e32 v5, 0xc0, v5
	v_sub_u32_e32 v1, v1, v5
	v_mov_b32_e32 v9, 1
	v_lshlrev_b32_e32 v5, 1, v4
	v_lshrrev_b32_e32 v7, 2, v4
	v_and_b32_e32 v8, 3, v6
	s_mov_b32 s2, 0x1fffe0
	v_lshlrev_b32_e32 v3, 5, v3
	v_ashrrev_i16_sdwa v1, v9, sext(v1) dst_sel:DWORD dst_unused:UNUSED_PAD src0_sel:DWORD src1_sel:BYTE_0
	v_and_b32_e32 v5, 24, v5
	v_and_b32_e32 v7, 4, v7
	v_and_or_b32 v8, v4, s2, v8
	v_and_b32_e32 v6, 1, v6
	v_and_b32_e32 v3, 32, v3
	v_bfe_i32 v1, v1, 0, 16
	v_or3_b32 v5, v8, v7, v5
	v_cmp_eq_u32_e32 vcc, 1, v6
	v_mov_b32_e32 v8, 0x20800
	v_lshlrev_b32_e32 v4, 17, v4
	v_cndmask_b32_e32 v6, 0, v8, vcc
	v_add_lshl_u32 v1, v3, v1, 1
	v_add3_u32 v129, v4, v6, v1
	v_lshl_add_u32 v130, v5, 11, v1
	v_add_u32_e32 v1, 0x2000, v2
	v_ashrrev_i32_e32 v2, 31, v1
	v_lshrrev_b32_e32 v2, 22, v2
	v_add_u32_e32 v2, v1, v2
	v_ashrrev_i32_e32 v2, 10, v2
	v_mul_i32_i24_e32 v3, 0x400, v2
	v_sub_u32_e32 v1, v1, v3
	v_readlane_b32 s4, v252, 21
	v_lshrrev_b32_e32 v3, 4, v1
	v_readlane_b32 s5, v252, 22
	s_add_u32 s44, s79, s4
	v_bitop3_b32 v1, v3, v1, 32 bitop3:0x6c
	s_addc_u32 s45, s40, s5
	v_readlane_b32 s4, v252, 17
	v_ashrrev_i32_e32 v4, 31, v1
	v_readlane_b32 s5, v252, 18
	s_add_u32 s4, s41, s4
	v_lshrrev_b32_e32 v4, 26, v4
	s_addc_u32 s5, s19, s5
	v_lshlrev_b32_e32 v3, 3, v2
	v_add_u32_e32 v4, v1, v4
	s_add_u32 s50, s4, 0xfffff800
	v_and_b32_e32 v3, -16, v3
	v_ashrrev_i32_e32 v5, 6, v4
	s_addc_u32 s51, s5, -1
	v_add_u32_e32 v3, v5, v3
	v_and_b32_e32 v7, 3, v5
	s_ashr_i32 s16, s0, 6
	v_and_or_b32 v7, v3, s2, v7
	s_lshl_b32 s2, s16, 10
	s_ashr_i32 s1, s0, 8
	v_and_b32_e32 v4, 0xc0, v4
	s_add_i32 s2, s2, 0
	v_sub_u32_e32 v1, v1, v4
	s_add_u32 s14, s4, 0xfff800
	v_lshlrev_b32_e32 v2, 5, v2
	v_ashrrev_i16_sdwa v1, v9, sext(v1) dst_sel:DWORD dst_unused:UNUSED_PAD src0_sel:DWORD src1_sel:BYTE_0
	v_lshlrev_b32_e32 v4, 1, v3
	v_lshrrev_b32_e32 v6, 2, v3
	s_addc_u32 s15, s5, 0
	v_and_b32_e32 v2, 32, v2
	v_bfe_i32 v1, v1, 0, 16
	v_and_b32_e32 v4, 24, v4
	v_and_b32_e32 v6, 4, v6
	s_add_u32 s22, s44, 0x40000
	v_or3_b32 v4, v7, v6, v4
	v_add_lshl_u32 v1, v2, v1, 1
	s_addc_u32 s23, s45, 0
	s_add_i32 s62, s2, 0x10000
	s_mov_b32 s6, m0
	s_mov_b32 m0, s62
	s_nop 0
	global_load_lds_dwordx4 v130, s[44:45]
	s_mov_b32 m0, s6
	v_lshl_add_u32 v132, v4, 11, v1
	s_add_i32 s63, s2, 0x12000
	s_mov_b32 s6, m0
	s_mov_b32 m0, s63
	s_nop 0
	global_load_lds_dwordx4 v132, s[44:45]
	s_mov_b32 m0, s6
	v_and_b32_e32 v5, 1, v5
	s_add_i32 s64, s2, 0x14000
	s_mov_b32 s6, m0
	s_mov_b32 m0, s64
	s_nop 0
	global_load_lds_dwordx4 v130, s[22:23]
	s_mov_b32 m0, s6
	v_cmp_eq_u32_e32 vcc, 1, v5
	s_add_i32 s68, s2, 0x16000
	s_mov_b32 s6, m0
	s_mov_b32 m0, s68
	s_nop 0
	global_load_lds_dwordx4 v132, s[22:23]
	s_mov_b32 m0, s6
	v_lshlrev_b32_e32 v3, 17, v3
	v_cndmask_b32_e32 v5, 0, v8, vcc
	s_mov_b32 s6, m0
	s_mov_b32 m0, s2
	s_nop 0
	global_load_lds_dwordx4 v129, s[50:51]
	s_mov_b32 m0, s6
	v_add3_u32 v131, v3, v5, v1
	s_add_i32 s69, s2, 0x2000
	s_mov_b32 s6, m0
	s_mov_b32 m0, s69
	s_nop 0
	global_load_lds_dwordx4 v131, s[50:51]
	s_mov_b32 m0, s6
	s_add_i32 s72, s2, 0x4000
	s_mov_b32 s6, m0
	s_mov_b32 m0, s72
	s_nop 0
	global_load_lds_dwordx4 v129, s[14:15]
	s_mov_b32 m0, s6
	s_add_i32 s73, s2, 0x6000
	s_mov_b32 s6, m0
	s_mov_b32 m0, s73
	s_nop 0
	global_load_lds_dwordx4 v131, s[14:15]
	s_mov_b32 m0, s6
	s_cmp_eq_u32 s1, 1
	s_cselect_b64 s[14:15], -1, 0
	s_setprio 1
	s_cmp_lg_u32 s1, 1
	s_cbranch_scc1 .LBB0_989
	s_barrier
	s_setprio 0

; __device__ __forceinline__ int mk_lane() { int l; asm volatile("v_mbcnt_lo_u32_b32 %0, -1, 0\n\tv_mbcnt_hi_u32_b32 %0, -1, %0" : "=v"(l)); return l; }
; #define PG8_STAGE(bufoff, gbase, voff) do { _Pragma("unroll") for (int _i = 0; _i < 2; ++_i) glds16_s((gbase), (voff)[_i], ldsb + (unsigned)((bufoff) + _i * 8192)); } while (0)
; #define PG8_WAIT_V(n) asm volatile("s_waitcnt vmcnt(" #n ")" ::: "memory")
; template <class Prob, class Epi, bool I8 = false, bool ALIGN_EPI = true, bool SP2 = true>
; __device__ __forceinline__ void gemm_phase(LAS unsigned char* lds, int wave, const Prob& P, const Epi& E) {
;     const int tid_ = wave * 64 + mk_lane();
;     const int tid = tid_, wid = __builtin_amdgcn_readfirstlane(tid >> 6), lane = tid & 63, wr = wid >> 2, wc = wid & 3, fr = lane & 15, fq = lane >> 4;
;     const int K = P.K, nt = K / BK;
;     unsigned voffA[2], voffB[2];
; #pragma unroll
;     for (int i = 0; i < 2; ++i) { int R, C; stage_rc(tid * 16 + i * 8192, R, C); const int Rb = (R & ~31) + perm32(R & 31);
;         voffA[i] = P.a_rowoff(R) + (unsigned)C * 2u; voffB[i] = P.b_rowoff(Rb) + (unsigned)C * 2u; }
;     const size_t kstep = (size_t)(BK * 2);
;     const size_t hstepA = P.a_hstep(), hstepB = P.b_hstep();
;     const unsigned ldsw = (unsigned)wid * 1024u;
;     const unsigned ldsb = (unsigned)(size_t)lds + ldsw;
;     const int aoff = lds_byte(wr * 64 + fr, fq * 8), boff = lds_byte(wc * 32 + fr, fq * 8);
;     ...
;     Unit cur, nxt; int ui = 0;
;     if (!P.next(0, cur)) return;
;     Acc acc;
; #pragma unroll
;     for (int a = 0; a < 2; ++a)
; #pragma unroll
;         for (int b = 0; b < 2; ++b)
; #pragma unroll
;             for (int m = 0; m < 4; ++m)
; #pragma unroll
;                 for (int n = 0; n < 2; ++n) acc[a][b][m][n] = (f32x4){0.f, 0.f, 0.f, 0.f};
;     h16x8 At[4][2], B0[2][2], B1[2][2];
;     const char* cA = P.a_tile(cur); const char* cB = P.b_tile(cur);
;     if constexpr (SP2) {
;         PG8_STAGE(PG8_SB(0, 0), cB, voffB); PG8_STAGE(PG8_SB(0, 1), cB + hstepB, voffB); PG8_STAGE(PG8_SA(0, 0), cA, voffA); PG8_STAGE(PG8_SA(0, 1), cA + hstepA, voffA);
;         if (wr == 1) PG8_BAR;
;         PG8_WAIT_V(2); PG8_BAR;
;         PG8_STAGE(PG8_SB(1, 0), cB + kstep, voffB); PG8_STAGE(PG8_SA(1, 0), cA + kstep, voffA); PG8_STAGE(PG8_SB(1, 1), cB + hstepB + kstep, voffB);
;         PG8_WAIT_V(6); PG8_BAR;
.LBB0_1056:
	v_readlane_b32 s0, v254, 42
	v_readlane_b32 s4, v252, 23
	s_waitcnt lgkmcnt(0)
	s_barrier
	s_add_u32 s14, s30, 0x2d200000
	v_mbcnt_lo_u32_b32 v0, -1, 0
	v_mbcnt_hi_u32_b32 v0, -1, v0
	v_readlane_b32 s5, v252, 24
	v_add_u32_e32 v1, s0, v0
	s_addc_u32 s15, s31, 0
	v_readfirstlane_b32 s0, v1
	s_and_b64 vcc, exec, s[4:5]
	s_cbranch_vccz .LBB0_1088
	v_ashrrev_i32_e32 v3, 31, v1
	v_lshrrev_b32_e32 v3, 26, v3
	v_lshlrev_b32_e32 v2, 4, v1
	v_add_u32_e32 v3, v1, v3
	v_bfe_i32 v1, v1, 27, 1
	v_lshrrev_b32_e32 v1, 22, v1
	v_add_u32_e32 v1, v2, v1
	v_and_b32_e32 v1, 0xfffffc00, v1
	v_sub_u32_e32 v1, v2, v1
	v_lshrrev_b32_e32 v4, 4, v1
	v_bitop3_b32 v1, v4, v1, 32 bitop3:0x6c
	v_ashrrev_i32_e32 v5, 31, v1
	v_ashrrev_i32_e32 v3, 6, v3
	v_lshrrev_b32_e32 v5, 26, v5
	v_lshlrev_b32_e32 v4, 3, v3
	v_add_u32_e32 v5, v1, v5
	v_and_b32_e32 v4, -16, v4
	v_ashrrev_i32_e32 v6, 6, v5
	v_add_u32_e32 v4, v6, v4
	v_and_b32_e32 v5, 0xc0, v5
	v_sub_u32_e32 v1, v1, v5
	v_lshlrev_b32_e32 v5, 1, v4
	v_lshrrev_b32_e32 v8, 2, v4
	v_and_b32_e32 v6, 3, v6
	s_mov_b32 s1, 0x1fffe0
	v_mov_b32_e32 v9, 1
	v_and_b32_e32 v7, 24, v5
	v_and_b32_e32 v8, 4, v8
	v_and_or_b32 v6, v4, s1, v6
	v_lshlrev_b32_e32 v3, 5, v3
	v_ashrrev_i16_sdwa v1, v9, sext(v1) dst_sel:DWORD dst_unused:UNUSED_PAD src0_sel:DWORD src1_sel:BYTE_0
	v_or3_b32 v6, v6, v8, v7
	v_lshlrev_b32_e32 v7, 3, v4
	v_and_b32_e32 v3, 32, v3
	v_bfe_i32 v1, v1, 0, 16
	v_and_b32_e32 v5, 0x1fff80, v5
	v_and_b32_e32 v7, 0x78, v7
	v_bfe_u32 v4, v4, 4, 2
	v_or3_b32 v4, v5, v7, v4
	v_add_lshl_u32 v1, v3, v1, 1
	v_lshl_add_u32 v250, v4, 11, v1
	v_lshl_add_u32 v217, v6, 11, v1
	v_add_u32_e32 v1, 0x2000, v2
	v_ashrrev_i32_e32 v2, 31, v1
	v_lshrrev_b32_e32 v2, 22, v2
	v_add_u32_e32 v2, v1, v2
	v_ashrrev_i32_e32 v2, 10, v2
	v_mul_i32_i24_e32 v3, 0x400, v2
	v_sub_u32_e32 v1, v1, v3
	v_lshrrev_b32_e32 v3, 4, v1
	v_bitop3_b32 v1, v3, v1, 32 bitop3:0x6c
	v_ashrrev_i32_e32 v4, 31, v1
	v_lshrrev_b32_e32 v4, 26, v4
	v_lshlrev_b32_e32 v3, 3, v2
	v_add_u32_e32 v4, v1, v4
	v_and_b32_e32 v3, -16, v3
	v_ashrrev_i32_e32 v5, 6, v4
	v_add_u32_e32 v3, v5, v3
	v_and_b32_e32 v5, 3, v5
	v_and_b32_e32 v4, 0xc0, v4
	v_and_or_b32 v5, v3, s1, v5
	s_ashr_i32 s1, s0, 6
	v_sub_u32_e32 v1, v1, v4
	s_lshl_b32 s2, s1, 10
	s_ashr_i32 s64, s0, 8
	v_lshlrev_b32_e32 v2, 5, v2
	v_ashrrev_i16_sdwa v1, v9, sext(v1) dst_sel:DWORD dst_unused:UNUSED_PAD src0_sel:DWORD src1_sel:BYTE_0
	v_lshlrev_b32_e32 v4, 1, v3
	v_lshrrev_b32_e32 v7, 2, v3
	s_add_i32 s72, s2, 0
	v_readlane_b32 s4, v252, 48
	v_and_b32_e32 v2, 32, v2
	v_bfe_i32 v1, v1, 0, 16
	v_and_b32_e32 v6, 24, v4
	v_and_b32_e32 v7, 4, v7
	v_readlane_b32 s5, v252, 49
	s_add_u32 s44, s79, s4
	v_or3_b32 v5, v5, v7, v6
	v_add_lshl_u32 v1, v2, v1, 1
	s_addc_u32 s45, s40, s5
	s_add_i32 s73, s72, 0x10000
	s_mov_b32 s2, m0
	s_mov_b32 m0, s73
	s_nop 0
	global_load_lds_dwordx4 v217, s[44:45]
	s_mov_b32 m0, s2
	s_add_i32 s74, s72, 0x12000
	v_lshl_add_u32 v248, v5, 11, v1
	s_mov_b32 s2, m0
	s_mov_b32 m0, s74
	s_nop 0
	global_load_lds_dwordx4 v248, s[44:45]
	s_mov_b32 m0, s2
	s_add_u32 s4, s44, 0x40000
	s_addc_u32 s5, s45, 0
	s_add_i32 s75, s72, 0x14000
	s_mov_b32 s2, m0
	s_mov_b32 m0, s75
	s_nop 0
	global_load_lds_dwordx4 v217, s[4:5]
	s_mov_b32 m0, s2
	v_lshlrev_b32_e32 v6, 3, v3
	s_add_i32 s80, s72, 0x16000
	s_mov_b32 s2, m0
	s_mov_b32 m0, s80
	s_nop 0
	global_load_lds_dwordx4 v248, s[4:5]
	s_mov_b32 m0, s2
	v_readlane_b32 s4, v252, 56
	v_and_b32_e32 v4, 0x1fff80, v4
	v_and_b32_e32 v6, 0x78, v6
	v_bfe_u32 v3, v3, 4, 2
	v_readlane_b32 s5, v252, 57
	s_add_u32 s60, s41, s4
	v_or3_b32 v3, v4, v6, v3
	s_addc_u32 s61, s19, s5
	s_mov_b32 s2, m0
	s_mov_b32 m0, s72
	s_nop 0
	global_load_lds_dwordx4 v250, s[60:61]
	s_mov_b32 m0, s2
	s_add_i32 s81, s72, 0x2000
	v_lshl_add_u32 v247, v3, 11, v1
	s_mov_b32 s2, m0
	s_mov_b32 m0, s81
	s_nop 0
	global_load_lds_dwordx4 v247, s[60:61]
	s_mov_b32 m0, s2
	s_add_u32 s4, s60, 0x2000
	s_addc_u32 s5, s61, 0
	s_add_i32 s82, s72, 0x4000
	s_mov_b32 s2, m0
	s_mov_b32 m0, s82
	s_nop 0
	global_load_lds_dwordx4 v250, s[4:5]
	s_mov_b32 m0, s2
	s_add_i32 s83, s72, 0x6000
	s_mov_b32 s2, m0
	s_mov_b32 m0, s83
	s_nop 0
	global_load_lds_dwordx4 v247, s[4:5]
	s_mov_b32 m0, s2
	s_cmp_eq_u32 s64, 1
	s_cselect_b64 s[16:17], -1, 0
	s_setprio 1
	s_cmp_lg_u32 s64, 1
	s_cbranch_scc1 .LBB0_1059
	s_barrier
	s_setprio 0

; __device__ __forceinline__ int mk_lane() { int l; asm volatile("v_mbcnt_lo_u32_b32 %0, -1, 0\n\tv_mbcnt_hi_u32_b32 %0, -1, %0" : "=v"(l)); return l; }
; #define PG8_STAGE(bufoff, gbase, voff) do { _Pragma("unroll") for (int _i = 0; _i < 2; ++_i) glds16_s((gbase), (voff)[_i], ldsb + (unsigned)((bufoff) + _i * 8192)); } while (0)
; #define PG8_WAIT_V(n) asm volatile("s_waitcnt vmcnt(" #n ")" ::: "memory")
; template <class Prob, class Epi, bool I8 = false, bool ALIGN_EPI = true, bool SP2 = true>
; __device__ __forceinline__ void gemm_phase(LAS unsigned char* lds, int wave, const Prob& P, const Epi& E) {
;     const int tid_ = wave * 64 + mk_lane();
;     const int tid = tid_, wid = __builtin_amdgcn_readfirstlane(tid >> 6), lane = tid & 63, wr = wid >> 2, wc = wid & 3, fr = lane & 15, fq = lane >> 4;
;     const int K = P.K, nt = K / BK;
;     unsigned voffA[2], voffB[2];
; #pragma unroll
;     for (int i = 0; i < 2; ++i) { int R, C; stage_rc(tid * 16 + i * 8192, R, C); const int Rb = (R & ~31) + perm32(R & 31);
;         voffA[i] = P.a_rowoff(R) + (unsigned)C * 2u; voffB[i] = P.b_rowoff(Rb) + (unsigned)C * 2u; }
;     const size_t kstep = (size_t)(BK * 2);
;     const size_t hstepA = P.a_hstep(), hstepB = P.b_hstep();
;     const unsigned ldsw = (unsigned)wid * 1024u;
;     const unsigned ldsb = (unsigned)(size_t)lds + ldsw;
;     const int aoff = lds_byte(wr * 64 + fr, fq * 8), boff = lds_byte(wc * 32 + fr, fq * 8);
;     ...
;     Unit cur, nxt; int ui = 0;
;     if (!P.next(0, cur)) return;
;     Acc acc;
; #pragma unroll
;     for (int a = 0; a < 2; ++a)
; #pragma unroll
;         for (int b = 0; b < 2; ++b)
; #pragma unroll
;             for (int m = 0; m < 4; ++m)
; #pragma unroll
;                 for (int n = 0; n < 2; ++n) acc[a][b][m][n] = (f32x4){0.f, 0.f, 0.f, 0.f};
;     h16x8 At[4][2], B0[2][2], B1[2][2];
;     const char* cA = P.a_tile(cur); const char* cB = P.b_tile(cur);
;     if constexpr (SP2) {
;         PG8_STAGE(PG8_SB(0, 0), cB, voffB); PG8_STAGE(PG8_SB(0, 1), cB + hstepB, voffB); PG8_STAGE(PG8_SA(0, 0), cA, voffA); PG8_STAGE(PG8_SA(0, 1), cA + hstepA, voffA);
;         if (wr == 1) PG8_BAR;
;         PG8_WAIT_V(2); PG8_BAR;
;         PG8_STAGE(PG8_SB(1, 0), cB + kstep, voffB); PG8_STAGE(PG8_SA(1, 0), cA + kstep, voffA); PG8_STAGE(PG8_SB(1, 1), cB + hstepB + kstep, voffB);
;         PG8_WAIT_V(6); PG8_BAR;
.LBB0_1203:
	v_readlane_b32 s0, v254, 42
	v_readlane_b32 s4, v254, 43
	s_waitcnt lgkmcnt(0)
	s_barrier
	v_mbcnt_lo_u32_b32 v0, -1, 0
	v_mbcnt_hi_u32_b32 v0, -1, v0
	v_readlane_b32 s5, v254, 44
	v_add_u32_e32 v1, s0, v0
	s_and_b64 vcc, exec, s[4:5]
	v_readfirstlane_b32 s0, v1
	s_cbranch_vccz .LBB0_1223
	v_ashrrev_i32_e32 v2, 31, v1
	v_lshrrev_b32_e32 v2, 26, v2
	v_lshlrev_b32_e32 v3, 4, v1
	v_add_u32_e32 v2, v1, v2
	v_bfe_i32 v1, v1, 27, 1
	v_lshrrev_b32_e32 v1, 22, v1
	v_add_u32_e32 v1, v3, v1
	v_and_b32_e32 v1, 0xfffffc00, v1
	v_sub_u32_e32 v1, v3, v1
	v_lshrrev_b32_e32 v4, 4, v1
	v_bitop3_b32 v1, v4, v1, 32 bitop3:0x6c
	v_ashrrev_i32_e32 v5, 31, v1
	v_lshrrev_b32_e32 v5, 26, v5
	v_ashrrev_i32_e32 v2, 6, v2
	v_add_u32_e32 v5, v1, v5
	v_readlane_b32 s1, v255, 1
	v_lshlrev_b32_e32 v4, 3, v2
	v_ashrrev_i32_e32 v6, 6, v5
	v_and_b32_e32 v5, 0xc0, v5
	s_mul_i32 s1, s1, 0xb00000
	v_and_b32_e32 v4, -16, v4
	v_sub_u32_e32 v1, v1, v5
	v_mov_b32_e32 v8, 1
	s_add_u32 s1, s30, s1
	v_add_u32_e32 v4, v6, v4
	v_lshlrev_b32_e32 v2, 5, v2
	v_ashrrev_i16_sdwa v1, v8, sext(v1) dst_sel:DWORD dst_unused:UNUSED_PAD src0_sel:DWORD src1_sel:BYTE_0
	s_addc_u32 s4, s31, 0
	v_and_b32_e32 v2, 32, v2
	v_bfe_i32 v1, v1, 0, 16
	v_lshlrev_b32_e32 v5, 1, v4
	v_lshrrev_b32_e32 v7, 2, v4
	v_and_b32_e32 v6, 3, v6
	s_mov_b32 s7, 0x7fffe0
	s_add_u32 s2, s1, 0xba00000
	v_and_b32_e32 v5, 24, v5
	v_and_b32_e32 v7, 4, v7
	v_and_or_b32 v6, v4, s7, v6
	v_add_lshl_u32 v2, v2, v1, 1
	s_movk_i32 s6, 0x1600
	s_addc_u32 s19, s4, 0
	v_or3_b32 v5, v6, v7, v5
	v_mad_u64_u32 v[160:161], s[4:5], v4, s6, v[2:3]
	v_add_u32_e32 v1, 0x2000, v3
	v_mad_u32_u24 v161, v5, s6, v2
	v_ashrrev_i32_e32 v2, 31, v1
	v_lshrrev_b32_e32 v2, 22, v2
	v_add_u32_e32 v2, v1, v2
	v_ashrrev_i32_e32 v2, 10, v2
	v_mul_i32_i24_e32 v3, 0x400, v2
	v_sub_u32_e32 v1, v1, v3
	v_lshrrev_b32_e32 v3, 4, v1
	v_bitop3_b32 v1, v3, v1, 32 bitop3:0x6c
	v_ashrrev_i32_e32 v4, 31, v1
	v_lshrrev_b32_e32 v4, 26, v4
	v_add_u32_e32 v4, v1, v4
	v_ashrrev_i32_e32 v5, 6, v4
	v_and_b32_e32 v4, 0xc0, v4
	v_lshlrev_b32_e32 v3, 3, v2
	v_sub_u32_e32 v1, v1, v4
	v_and_b32_e32 v3, -16, v3
	v_lshlrev_b32_e32 v2, 5, v2
	v_ashrrev_i16_sdwa v1, v8, sext(v1) dst_sel:DWORD dst_unused:UNUSED_PAD src0_sel:DWORD src1_sel:BYTE_0
	v_add_u32_e32 v3, v5, v3
	v_and_b32_e32 v2, 32, v2
	v_bfe_i32 v1, v1, 0, 16
	v_lshlrev_b32_e32 v4, 1, v3
	v_lshrrev_b32_e32 v6, 2, v3
	v_and_b32_e32 v5, 3, v5
	v_add_lshl_u32 v2, v2, v1, 1
	v_and_b32_e32 v4, 24, v4
	v_and_b32_e32 v6, 4, v6
	v_and_or_b32 v5, v3, s7, v5
	v_mad_u64_u32 v[162:163], s[4:5], v3, s6, v[2:3]
	v_or3_b32 v4, v5, v6, v4
	s_ashr_i32 s4, s0, 6
	v_mad_u32_u24 v163, v4, s6, v2
	s_lshl_b32 s5, s4, 10
	v_readlane_b32 s6, v252, 31
	s_ashr_i32 s1, s0, 8
	s_add_i32 s40, s5, 0
	s_mul_i32 s5, s6, 0x160000
	s_add_u32 s14, s2, s5
	s_mul_hi_i32 s5, s6, 0x160000
	s_addc_u32 s15, s19, s5
	s_add_i32 s41, s40, 0x10000
	s_mov_b32 s5, m0
	s_mov_b32 m0, s41
	s_nop 0
	global_load_lds_dwordx4 v161, s[14:15]
	s_mov_b32 m0, s5
	s_add_i32 s62, s40, 0x12000
	s_mov_b32 s5, m0
	s_mov_b32 m0, s62
	s_nop 0
	global_load_lds_dwordx4 v163, s[14:15]
	s_mov_b32 m0, s5
	s_add_u32 s6, s14, 0xb0000
	s_addc_u32 s7, s15, 0
	s_add_i32 s63, s40, 0x14000
	s_mov_b32 s5, m0
	s_mov_b32 m0, s63
	s_nop 0
	global_load_lds_dwordx4 v161, s[6:7]
	s_mov_b32 m0, s5
	s_add_i32 s64, s40, 0x16000
	s_mov_b32 s5, m0
	s_mov_b32 m0, s64
	s_nop 0
	global_load_lds_dwordx4 v163, s[6:7]
	s_mov_b32 m0, s5
	v_readlane_b32 s6, v252, 42
	v_readlane_b32 s7, v252, 43
	s_mov_b32 s5, m0
	s_mov_b32 m0, s40
	s_nop 0
	global_load_lds_dwordx4 v160, s[6:7]
	s_mov_b32 m0, s5
	s_add_i32 s68, s40, 0x2000
	s_mov_b32 s5, m0
	s_mov_b32 m0, s68
	s_nop 0
	global_load_lds_dwordx4 v162, s[6:7]
	s_mov_b32 m0, s5
	v_readlane_b32 s6, v252, 40
	s_add_i32 s69, s40, 0x4000
	v_readlane_b32 s7, v252, 41
	s_mov_b32 s5, m0
	s_mov_b32 m0, s69
	s_nop 0
	global_load_lds_dwordx4 v160, s[6:7]
	s_mov_b32 m0, s5
	s_add_i32 s76, s40, 0x6000
	s_mov_b32 s5, m0
	s_mov_b32 m0, s76
	s_nop 0
	global_load_lds_dwordx4 v162, s[6:7]
	s_mov_b32 m0, s5
	s_cmp_eq_u32 s1, 1
	s_cselect_b64 s[16:17], -1, 0
	s_setprio 1
	s_cmp_lg_u32 s1, 1
	s_cbranch_scc1 .LBB0_1206
	s_barrier
	s_setprio 0
